# adds hand-written P4 mid-K gate hook (12 gate loads in flight per wave) to the stack
# baseline (speedup 1.0000x reference)
.LBB0_524:
	v_cndmask_b32_e64 v3, 0, 1, s[62:63]
	v_cmp_ne_u32_e64 s[4:5], 1, v3
	s_andn2_b64 vcc, exec, s[62:63]
	s_cbranch_vccnz .LBB0_526
	v_mov_b32_e32 v4, v164
	v_ashrrev_i32_e32 v5, 31, v4
	v_lshlrev_b64 v[4:5], 11, v[4:5]
	v_lshl_add_u64 v[4:5], v[4:5], 0, v[162:163]
	v_lshlrev_b64 v[4:5], 1, v[4:5]
	v_lshl_add_u64 v[200:201], s[38:39], 0, v[4:5]
	v_lshl_add_u64 v[202:203], s[14:15], 0, v[4:5]
	global_load_dwordx4 v[134:137], v[200:201], off
	global_load_dwordx4 v[138:141], v[202:203], off
	global_load_dwordx4 v[142:145], v[200:201], off offset:256
	global_load_dwordx4 v[146:149], v[202:203], off offset:256
	v_lshl_add_u64 v[198:199], v[4:5], 0, s[30:31]
	v_lshl_add_u64 v[200:201], s[38:39], 0, v[198:199]
	v_lshl_add_u64 v[202:203], s[14:15], 0, v[198:199]
	global_load_dwordx4 v[150:153], v[200:201], off
	global_load_dwordx4 v[154:157], v[202:203], off
	global_load_dwordx4 v[174:177], v[200:201], off offset:256
	global_load_dwordx4 v[178:181], v[202:203], off offset:256
	v_lshl_add_u64 v[198:199], v[4:5], 0, s[42:43]
	v_lshl_add_u64 v[200:201], s[38:39], 0, v[198:199]
	v_lshl_add_u64 v[202:203], s[14:15], 0, v[198:199]
	global_load_dwordx4 v[182:185], v[200:201], off
	global_load_dwordx4 v[186:189], v[202:203], off
	global_load_dwordx4 v[190:193], v[200:201], off offset:256
	global_load_dwordx4 v[194:197], v[202:203], off offset:256
	s_waitcnt vmcnt(8)
	v_lshlrev_b32_e32 v204, 16, v134
	v_and_b32_e32 v205, 0xffff0000, v134
	v_rcp_f32_e32 v204, v204
	v_rcp_f32_e32 v205, v205
	v_lshlrev_b32_e32 v206, 16, v138
	v_and_b32_e32 v207, 0xffff0000, v138
	v_pk_mul_f32 v[204:205], v[206:207], v[204:205]
	v_pk_mul_f32 v[130:131], v[130:131], v[204:205]
	v_lshlrev_b32_e32 v204, 16, v135
	v_and_b32_e32 v205, 0xffff0000, v135
	v_rcp_f32_e32 v204, v204
	v_rcp_f32_e32 v205, v205
	v_lshlrev_b32_e32 v206, 16, v139
	v_and_b32_e32 v207, 0xffff0000, v139
	v_pk_mul_f32 v[204:205], v[206:207], v[204:205]
	v_pk_mul_f32 v[132:133], v[132:133], v[204:205]
	v_lshlrev_b32_e32 v204, 16, v136
	v_and_b32_e32 v205, 0xffff0000, v136
	v_rcp_f32_e32 v204, v204
	v_rcp_f32_e32 v205, v205
	v_lshlrev_b32_e32 v206, 16, v140
	v_and_b32_e32 v207, 0xffff0000, v140
	v_pk_mul_f32 v[204:205], v[206:207], v[204:205]
	v_pk_mul_f32 v[126:127], v[126:127], v[204:205]
	v_lshlrev_b32_e32 v204, 16, v137
	v_and_b32_e32 v205, 0xffff0000, v137
	v_rcp_f32_e32 v204, v204
	v_rcp_f32_e32 v205, v205
	v_lshlrev_b32_e32 v206, 16, v141
	v_and_b32_e32 v207, 0xffff0000, v141
	v_pk_mul_f32 v[204:205], v[206:207], v[204:205]
	v_pk_mul_f32 v[128:129], v[128:129], v[204:205]
	v_lshlrev_b32_e32 v204, 16, v142
	v_and_b32_e32 v205, 0xffff0000, v142
	v_rcp_f32_e32 v204, v204
	v_rcp_f32_e32 v205, v205
	v_lshlrev_b32_e32 v206, 16, v146
	v_and_b32_e32 v207, 0xffff0000, v146
	v_pk_mul_f32 v[204:205], v[206:207], v[204:205]
	v_pk_mul_f32 v[122:123], v[122:123], v[204:205]
	v_lshlrev_b32_e32 v204, 16, v143
	v_and_b32_e32 v205, 0xffff0000, v143
	v_rcp_f32_e32 v204, v204
	v_rcp_f32_e32 v205, v205
	v_lshlrev_b32_e32 v206, 16, v147
	v_and_b32_e32 v207, 0xffff0000, v147
	v_pk_mul_f32 v[204:205], v[206:207], v[204:205]
	v_pk_mul_f32 v[124:125], v[124:125], v[204:205]
	v_lshlrev_b32_e32 v204, 16, v144
	v_and_b32_e32 v205, 0xffff0000, v144
	v_rcp_f32_e32 v204, v204
	v_rcp_f32_e32 v205, v205
	v_lshlrev_b32_e32 v206, 16, v148
	v_and_b32_e32 v207, 0xffff0000, v148
	v_pk_mul_f32 v[204:205], v[206:207], v[204:205]
	v_pk_mul_f32 v[118:119], v[118:119], v[204:205]
	v_lshlrev_b32_e32 v204, 16, v145
	v_and_b32_e32 v205, 0xffff0000, v145
	v_rcp_f32_e32 v204, v204
	v_rcp_f32_e32 v205, v205
	v_lshlrev_b32_e32 v206, 16, v149
	v_and_b32_e32 v207, 0xffff0000, v149
	v_pk_mul_f32 v[204:205], v[206:207], v[204:205]
	v_pk_mul_f32 v[120:121], v[120:121], v[204:205]
	v_lshl_add_u64 v[198:199], v[4:5], 0, s[46:47]
	v_lshl_add_u64 v[200:201], s[38:39], 0, v[198:199]
	v_lshl_add_u64 v[202:203], s[14:15], 0, v[198:199]
	global_load_dwordx4 v[134:137], v[200:201], off
	global_load_dwordx4 v[138:141], v[202:203], off
	global_load_dwordx4 v[142:145], v[200:201], off offset:256
	global_load_dwordx4 v[146:149], v[202:203], off offset:256
	s_waitcnt vmcnt(8)
	v_lshlrev_b32_e32 v204, 16, v150
	v_and_b32_e32 v205, 0xffff0000, v150
	v_rcp_f32_e32 v204, v204
	v_rcp_f32_e32 v205, v205
	v_lshlrev_b32_e32 v206, 16, v154
	v_and_b32_e32 v207, 0xffff0000, v154
	v_pk_mul_f32 v[204:205], v[206:207], v[204:205]
	v_pk_mul_f32 v[114:115], v[114:115], v[204:205]
	v_lshlrev_b32_e32 v204, 16, v151
	v_and_b32_e32 v205, 0xffff0000, v151
	v_rcp_f32_e32 v204, v204
	v_rcp_f32_e32 v205, v205
	v_lshlrev_b32_e32 v206, 16, v155
	v_and_b32_e32 v207, 0xffff0000, v155
	v_pk_mul_f32 v[204:205], v[206:207], v[204:205]
	v_pk_mul_f32 v[116:117], v[116:117], v[204:205]
	v_lshlrev_b32_e32 v204, 16, v152
	v_and_b32_e32 v205, 0xffff0000, v152
	v_rcp_f32_e32 v204, v204
	v_rcp_f32_e32 v205, v205
	v_lshlrev_b32_e32 v206, 16, v156
	v_and_b32_e32 v207, 0xffff0000, v156
	v_pk_mul_f32 v[204:205], v[206:207], v[204:205]
	v_pk_mul_f32 v[110:111], v[110:111], v[204:205]
	v_lshlrev_b32_e32 v204, 16, v153
	v_and_b32_e32 v205, 0xffff0000, v153
	v_rcp_f32_e32 v204, v204
	v_rcp_f32_e32 v205, v205
	v_lshlrev_b32_e32 v206, 16, v157
	v_and_b32_e32 v207, 0xffff0000, v157
	v_pk_mul_f32 v[204:205], v[206:207], v[204:205]
	v_pk_mul_f32 v[112:113], v[112:113], v[204:205]
	v_lshlrev_b32_e32 v204, 16, v174
	v_and_b32_e32 v205, 0xffff0000, v174
	v_rcp_f32_e32 v204, v204
	v_rcp_f32_e32 v205, v205
	v_lshlrev_b32_e32 v206, 16, v178
	v_and_b32_e32 v207, 0xffff0000, v178
	v_pk_mul_f32 v[204:205], v[206:207], v[204:205]
	v_pk_mul_f32 v[106:107], v[106:107], v[204:205]
	v_lshlrev_b32_e32 v204, 16, v175
	v_and_b32_e32 v205, 0xffff0000, v175
	v_rcp_f32_e32 v204, v204
	v_rcp_f32_e32 v205, v205
	v_lshlrev_b32_e32 v206, 16, v179
	v_and_b32_e32 v207, 0xffff0000, v179
	v_pk_mul_f32 v[204:205], v[206:207], v[204:205]
	v_pk_mul_f32 v[108:109], v[108:109], v[204:205]
	v_lshlrev_b32_e32 v204, 16, v176
	v_and_b32_e32 v205, 0xffff0000, v176
	v_rcp_f32_e32 v204, v204
	v_rcp_f32_e32 v205, v205
	v_lshlrev_b32_e32 v206, 16, v180
	v_and_b32_e32 v207, 0xffff0000, v180
	v_pk_mul_f32 v[204:205], v[206:207], v[204:205]
	v_pk_mul_f32 v[102:103], v[102:103], v[204:205]
	v_lshlrev_b32_e32 v204, 16, v177
	v_and_b32_e32 v205, 0xffff0000, v177
	v_rcp_f32_e32 v204, v204
	v_rcp_f32_e32 v205, v205
	v_lshlrev_b32_e32 v206, 16, v181
	v_and_b32_e32 v207, 0xffff0000, v181
	v_pk_mul_f32 v[204:205], v[206:207], v[204:205]
	v_pk_mul_f32 v[104:105], v[104:105], v[204:205]
	v_lshl_add_u64 v[198:199], v[4:5], 0, s[52:53]
	v_lshl_add_u64 v[200:201], s[38:39], 0, v[198:199]
	v_lshl_add_u64 v[202:203], s[14:15], 0, v[198:199]
	global_load_dwordx4 v[150:153], v[200:201], off
	global_load_dwordx4 v[154:157], v[202:203], off
	global_load_dwordx4 v[174:177], v[200:201], off offset:256
	global_load_dwordx4 v[178:181], v[202:203], off offset:256
	s_waitcnt vmcnt(8)
	v_lshlrev_b32_e32 v204, 16, v182
	v_and_b32_e32 v205, 0xffff0000, v182
	v_rcp_f32_e32 v204, v204
	v_rcp_f32_e32 v205, v205
	v_lshlrev_b32_e32 v206, 16, v186
	v_and_b32_e32 v207, 0xffff0000, v186
	v_pk_mul_f32 v[204:205], v[206:207], v[204:205]
	v_pk_mul_f32 v[98:99], v[98:99], v[204:205]
	v_lshlrev_b32_e32 v204, 16, v183
	v_and_b32_e32 v205, 0xffff0000, v183
	v_rcp_f32_e32 v204, v204
	v_rcp_f32_e32 v205, v205
	v_lshlrev_b32_e32 v206, 16, v187
	v_and_b32_e32 v207, 0xffff0000, v187
	v_pk_mul_f32 v[204:205], v[206:207], v[204:205]
	v_pk_mul_f32 v[100:101], v[100:101], v[204:205]
	v_lshlrev_b32_e32 v204, 16, v184
	v_and_b32_e32 v205, 0xffff0000, v184
	v_rcp_f32_e32 v204, v204
	v_rcp_f32_e32 v205, v205
	v_lshlrev_b32_e32 v206, 16, v188
	v_and_b32_e32 v207, 0xffff0000, v188
	v_pk_mul_f32 v[204:205], v[206:207], v[204:205]
	v_pk_mul_f32 v[94:95], v[94:95], v[204:205]
	v_lshlrev_b32_e32 v204, 16, v185
	v_and_b32_e32 v205, 0xffff0000, v185
	v_rcp_f32_e32 v204, v204
	v_rcp_f32_e32 v205, v205
	v_lshlrev_b32_e32 v206, 16, v189
	v_and_b32_e32 v207, 0xffff0000, v189
	v_pk_mul_f32 v[204:205], v[206:207], v[204:205]
	v_pk_mul_f32 v[96:97], v[96:97], v[204:205]
	v_lshlrev_b32_e32 v204, 16, v190
	v_and_b32_e32 v205, 0xffff0000, v190
	v_rcp_f32_e32 v204, v204
	v_rcp_f32_e32 v205, v205
	v_lshlrev_b32_e32 v206, 16, v194
	v_and_b32_e32 v207, 0xffff0000, v194
	v_pk_mul_f32 v[204:205], v[206:207], v[204:205]
	v_pk_mul_f32 v[90:91], v[90:91], v[204:205]
	v_lshlrev_b32_e32 v204, 16, v191
	v_and_b32_e32 v205, 0xffff0000, v191
	v_rcp_f32_e32 v204, v204
	v_rcp_f32_e32 v205, v205
	v_lshlrev_b32_e32 v206, 16, v195
	v_and_b32_e32 v207, 0xffff0000, v195
	v_pk_mul_f32 v[204:205], v[206:207], v[204:205]
	v_pk_mul_f32 v[92:93], v[92:93], v[204:205]
	v_lshlrev_b32_e32 v204, 16, v192
	v_and_b32_e32 v205, 0xffff0000, v192
	v_rcp_f32_e32 v204, v204
	v_rcp_f32_e32 v205, v205
	v_lshlrev_b32_e32 v206, 16, v196
	v_and_b32_e32 v207, 0xffff0000, v196
	v_pk_mul_f32 v[204:205], v[206:207], v[204:205]
	v_pk_mul_f32 v[86:87], v[86:87], v[204:205]
	v_lshlrev_b32_e32 v204, 16, v193
	v_and_b32_e32 v205, 0xffff0000, v193
	v_rcp_f32_e32 v204, v204
	v_rcp_f32_e32 v205, v205
	v_lshlrev_b32_e32 v206, 16, v197
	v_and_b32_e32 v207, 0xffff0000, v197
	v_pk_mul_f32 v[204:205], v[206:207], v[204:205]
	v_pk_mul_f32 v[88:89], v[88:89], v[204:205]
	v_lshl_add_u64 v[198:199], v[4:5], 0, s[56:57]
	v_lshl_add_u64 v[200:201], s[38:39], 0, v[198:199]
	v_lshl_add_u64 v[202:203], s[14:15], 0, v[198:199]
	global_load_dwordx4 v[182:185], v[200:201], off
	global_load_dwordx4 v[186:189], v[202:203], off
	global_load_dwordx4 v[190:193], v[200:201], off offset:256
	global_load_dwordx4 v[194:197], v[202:203], off offset:256
	s_waitcnt vmcnt(8)
	v_lshlrev_b32_e32 v204, 16, v134
	v_and_b32_e32 v205, 0xffff0000, v134
	v_rcp_f32_e32 v204, v204
	v_rcp_f32_e32 v205, v205
	v_lshlrev_b32_e32 v206, 16, v138
	v_and_b32_e32 v207, 0xffff0000, v138
	v_pk_mul_f32 v[204:205], v[206:207], v[204:205]
	v_pk_mul_f32 v[82:83], v[82:83], v[204:205]
	v_lshlrev_b32_e32 v204, 16, v135
	v_and_b32_e32 v205, 0xffff0000, v135
	v_rcp_f32_e32 v204, v204
	v_rcp_f32_e32 v205, v205
	v_lshlrev_b32_e32 v206, 16, v139
	v_and_b32_e32 v207, 0xffff0000, v139
	v_pk_mul_f32 v[204:205], v[206:207], v[204:205]
	v_pk_mul_f32 v[84:85], v[84:85], v[204:205]
	v_lshlrev_b32_e32 v204, 16, v136
	v_and_b32_e32 v205, 0xffff0000, v136
	v_rcp_f32_e32 v204, v204
	v_rcp_f32_e32 v205, v205
	v_lshlrev_b32_e32 v206, 16, v140
	v_and_b32_e32 v207, 0xffff0000, v140
	v_pk_mul_f32 v[204:205], v[206:207], v[204:205]
	v_pk_mul_f32 v[78:79], v[78:79], v[204:205]
	v_lshlrev_b32_e32 v204, 16, v137
	v_and_b32_e32 v205, 0xffff0000, v137
	v_rcp_f32_e32 v204, v204
	v_rcp_f32_e32 v205, v205
	v_lshlrev_b32_e32 v206, 16, v141
	v_and_b32_e32 v207, 0xffff0000, v141
	v_pk_mul_f32 v[204:205], v[206:207], v[204:205]
	v_pk_mul_f32 v[80:81], v[80:81], v[204:205]
	v_lshlrev_b32_e32 v204, 16, v142
	v_and_b32_e32 v205, 0xffff0000, v142
	v_rcp_f32_e32 v204, v204
	v_rcp_f32_e32 v205, v205
	v_lshlrev_b32_e32 v206, 16, v146
	v_and_b32_e32 v207, 0xffff0000, v146
	v_pk_mul_f32 v[204:205], v[206:207], v[204:205]
	v_pk_mul_f32 v[74:75], v[74:75], v[204:205]
	v_lshlrev_b32_e32 v204, 16, v143
	v_and_b32_e32 v205, 0xffff0000, v143
	v_rcp_f32_e32 v204, v204
	v_rcp_f32_e32 v205, v205
	v_lshlrev_b32_e32 v206, 16, v147
	v_and_b32_e32 v207, 0xffff0000, v147
	v_pk_mul_f32 v[204:205], v[206:207], v[204:205]
	v_pk_mul_f32 v[76:77], v[76:77], v[204:205]
	v_lshlrev_b32_e32 v204, 16, v144
	v_and_b32_e32 v205, 0xffff0000, v144
	v_rcp_f32_e32 v204, v204
	v_rcp_f32_e32 v205, v205
	v_lshlrev_b32_e32 v206, 16, v148
	v_and_b32_e32 v207, 0xffff0000, v148
	v_pk_mul_f32 v[204:205], v[206:207], v[204:205]
	v_pk_mul_f32 v[70:71], v[70:71], v[204:205]
	v_lshlrev_b32_e32 v204, 16, v145
	v_and_b32_e32 v205, 0xffff0000, v145
	v_rcp_f32_e32 v204, v204
	v_rcp_f32_e32 v205, v205
	v_lshlrev_b32_e32 v206, 16, v149
	v_and_b32_e32 v207, 0xffff0000, v149
	v_pk_mul_f32 v[204:205], v[206:207], v[204:205]
	v_pk_mul_f32 v[72:73], v[72:73], v[204:205]
	v_lshl_add_u64 v[198:199], v[4:5], 0, s[58:59]
	v_lshl_add_u64 v[200:201], s[38:39], 0, v[198:199]
	v_lshl_add_u64 v[202:203], s[14:15], 0, v[198:199]
	global_load_dwordx4 v[134:137], v[200:201], off
	global_load_dwordx4 v[138:141], v[202:203], off
	global_load_dwordx4 v[142:145], v[200:201], off offset:256
	global_load_dwordx4 v[146:149], v[202:203], off offset:256
	s_waitcnt vmcnt(8)
	v_lshlrev_b32_e32 v204, 16, v150
	v_and_b32_e32 v205, 0xffff0000, v150
	v_rcp_f32_e32 v204, v204
	v_rcp_f32_e32 v205, v205
	v_lshlrev_b32_e32 v206, 16, v154
	v_and_b32_e32 v207, 0xffff0000, v154
	v_pk_mul_f32 v[204:205], v[206:207], v[204:205]
	v_pk_mul_f32 v[66:67], v[66:67], v[204:205]
	v_lshlrev_b32_e32 v204, 16, v151
	v_and_b32_e32 v205, 0xffff0000, v151
	v_rcp_f32_e32 v204, v204
	v_rcp_f32_e32 v205, v205
	v_lshlrev_b32_e32 v206, 16, v155
	v_and_b32_e32 v207, 0xffff0000, v155
	v_pk_mul_f32 v[204:205], v[206:207], v[204:205]
	v_pk_mul_f32 v[68:69], v[68:69], v[204:205]
	v_lshlrev_b32_e32 v204, 16, v152
	v_and_b32_e32 v205, 0xffff0000, v152
	v_rcp_f32_e32 v204, v204
	v_rcp_f32_e32 v205, v205
	v_lshlrev_b32_e32 v206, 16, v156
	v_and_b32_e32 v207, 0xffff0000, v156
	v_pk_mul_f32 v[204:205], v[206:207], v[204:205]
	v_pk_mul_f32 v[62:63], v[62:63], v[204:205]
	v_lshlrev_b32_e32 v204, 16, v153
	v_and_b32_e32 v205, 0xffff0000, v153
	v_rcp_f32_e32 v204, v204
	v_rcp_f32_e32 v205, v205
	v_lshlrev_b32_e32 v206, 16, v157
	v_and_b32_e32 v207, 0xffff0000, v157
	v_pk_mul_f32 v[204:205], v[206:207], v[204:205]
	v_pk_mul_f32 v[64:65], v[64:65], v[204:205]
	v_lshlrev_b32_e32 v204, 16, v174
	v_and_b32_e32 v205, 0xffff0000, v174
	v_rcp_f32_e32 v204, v204
	v_rcp_f32_e32 v205, v205
	v_lshlrev_b32_e32 v206, 16, v178
	v_and_b32_e32 v207, 0xffff0000, v178
	v_pk_mul_f32 v[204:205], v[206:207], v[204:205]
	v_pk_mul_f32 v[58:59], v[58:59], v[204:205]
	v_lshlrev_b32_e32 v204, 16, v175
	v_and_b32_e32 v205, 0xffff0000, v175
	v_rcp_f32_e32 v204, v204
	v_rcp_f32_e32 v205, v205
	v_lshlrev_b32_e32 v206, 16, v179
	v_and_b32_e32 v207, 0xffff0000, v179
	v_pk_mul_f32 v[204:205], v[206:207], v[204:205]
	v_pk_mul_f32 v[60:61], v[60:61], v[204:205]
	v_lshlrev_b32_e32 v204, 16, v176
	v_and_b32_e32 v205, 0xffff0000, v176
	v_rcp_f32_e32 v204, v204
	v_rcp_f32_e32 v205, v205
	v_lshlrev_b32_e32 v206, 16, v180
	v_and_b32_e32 v207, 0xffff0000, v180
	v_pk_mul_f32 v[204:205], v[206:207], v[204:205]
	v_pk_mul_f32 v[54:55], v[54:55], v[204:205]
	v_lshlrev_b32_e32 v204, 16, v177
	v_and_b32_e32 v205, 0xffff0000, v177
	v_rcp_f32_e32 v204, v204
	v_rcp_f32_e32 v205, v205
	v_lshlrev_b32_e32 v206, 16, v181
	v_and_b32_e32 v207, 0xffff0000, v181
	v_pk_mul_f32 v[204:205], v[206:207], v[204:205]
	v_pk_mul_f32 v[56:57], v[56:57], v[204:205]
	v_lshl_add_u64 v[198:199], v[4:5], 0, s[60:61]
	v_lshl_add_u64 v[200:201], s[38:39], 0, v[198:199]
	v_lshl_add_u64 v[202:203], s[14:15], 0, v[198:199]
	global_load_dwordx4 v[150:153], v[200:201], off
	global_load_dwordx4 v[154:157], v[202:203], off
	global_load_dwordx4 v[174:177], v[200:201], off offset:256
	global_load_dwordx4 v[178:181], v[202:203], off offset:256
	s_waitcnt vmcnt(8)
	v_lshlrev_b32_e32 v204, 16, v182
	v_and_b32_e32 v205, 0xffff0000, v182
	v_rcp_f32_e32 v204, v204
	v_rcp_f32_e32 v205, v205
	v_lshlrev_b32_e32 v206, 16, v186
	v_and_b32_e32 v207, 0xffff0000, v186
	v_pk_mul_f32 v[204:205], v[206:207], v[204:205]
	v_pk_mul_f32 v[50:51], v[50:51], v[204:205]
	v_lshlrev_b32_e32 v204, 16, v183
	v_and_b32_e32 v205, 0xffff0000, v183
	v_rcp_f32_e32 v204, v204
	v_rcp_f32_e32 v205, v205
	v_lshlrev_b32_e32 v206, 16, v187
	v_and_b32_e32 v207, 0xffff0000, v187
	v_pk_mul_f32 v[204:205], v[206:207], v[204:205]
	v_pk_mul_f32 v[52:53], v[52:53], v[204:205]
	v_lshlrev_b32_e32 v204, 16, v184
	v_and_b32_e32 v205, 0xffff0000, v184
	v_rcp_f32_e32 v204, v204
	v_rcp_f32_e32 v205, v205
	v_lshlrev_b32_e32 v206, 16, v188
	v_and_b32_e32 v207, 0xffff0000, v188
	v_pk_mul_f32 v[204:205], v[206:207], v[204:205]
	v_pk_mul_f32 v[46:47], v[46:47], v[204:205]
	v_lshlrev_b32_e32 v204, 16, v185
	v_and_b32_e32 v205, 0xffff0000, v185
	v_rcp_f32_e32 v204, v204
	v_rcp_f32_e32 v205, v205
	v_lshlrev_b32_e32 v206, 16, v189
	v_and_b32_e32 v207, 0xffff0000, v189
	v_pk_mul_f32 v[204:205], v[206:207], v[204:205]
	v_pk_mul_f32 v[48:49], v[48:49], v[204:205]
	v_lshlrev_b32_e32 v204, 16, v190
	v_and_b32_e32 v205, 0xffff0000, v190
	v_rcp_f32_e32 v204, v204
	v_rcp_f32_e32 v205, v205
	v_lshlrev_b32_e32 v206, 16, v194
	v_and_b32_e32 v207, 0xffff0000, v194
	v_pk_mul_f32 v[204:205], v[206:207], v[204:205]
	v_pk_mul_f32 v[42:43], v[42:43], v[204:205]
	v_lshlrev_b32_e32 v204, 16, v191
	v_and_b32_e32 v205, 0xffff0000, v191
	v_rcp_f32_e32 v204, v204
	v_rcp_f32_e32 v205, v205
	v_lshlrev_b32_e32 v206, 16, v195
	v_and_b32_e32 v207, 0xffff0000, v195
	v_pk_mul_f32 v[204:205], v[206:207], v[204:205]
	v_pk_mul_f32 v[44:45], v[44:45], v[204:205]
	v_lshlrev_b32_e32 v204, 16, v192
	v_and_b32_e32 v205, 0xffff0000, v192
	v_rcp_f32_e32 v204, v204
	v_rcp_f32_e32 v205, v205
	v_lshlrev_b32_e32 v206, 16, v196
	v_and_b32_e32 v207, 0xffff0000, v196
	v_pk_mul_f32 v[204:205], v[206:207], v[204:205]
	v_pk_mul_f32 v[38:39], v[38:39], v[204:205]
	v_lshlrev_b32_e32 v204, 16, v193
	v_and_b32_e32 v205, 0xffff0000, v193
	v_rcp_f32_e32 v204, v204
	v_rcp_f32_e32 v205, v205
	v_lshlrev_b32_e32 v206, 16, v197
	v_and_b32_e32 v207, 0xffff0000, v197
	v_pk_mul_f32 v[204:205], v[206:207], v[204:205]
	v_pk_mul_f32 v[40:41], v[40:41], v[204:205]
	s_waitcnt vmcnt(4)
	v_lshlrev_b32_e32 v204, 16, v134
	v_and_b32_e32 v205, 0xffff0000, v134
	v_rcp_f32_e32 v204, v204
	v_rcp_f32_e32 v205, v205
	v_lshlrev_b32_e32 v206, 16, v138
	v_and_b32_e32 v207, 0xffff0000, v138
	v_pk_mul_f32 v[204:205], v[206:207], v[204:205]
	v_pk_mul_f32 v[34:35], v[34:35], v[204:205]
	v_lshlrev_b32_e32 v204, 16, v135
	v_and_b32_e32 v205, 0xffff0000, v135
	v_rcp_f32_e32 v204, v204
	v_rcp_f32_e32 v205, v205
	v_lshlrev_b32_e32 v206, 16, v139
	v_and_b32_e32 v207, 0xffff0000, v139
	v_pk_mul_f32 v[204:205], v[206:207], v[204:205]
	v_pk_mul_f32 v[36:37], v[36:37], v[204:205]
	v_lshlrev_b32_e32 v204, 16, v136
	v_and_b32_e32 v205, 0xffff0000, v136
	v_rcp_f32_e32 v204, v204
	v_rcp_f32_e32 v205, v205
	v_lshlrev_b32_e32 v206, 16, v140
	v_and_b32_e32 v207, 0xffff0000, v140
	v_pk_mul_f32 v[204:205], v[206:207], v[204:205]
	v_pk_mul_f32 v[30:31], v[30:31], v[204:205]
	v_lshlrev_b32_e32 v204, 16, v137
	v_and_b32_e32 v205, 0xffff0000, v137
	v_rcp_f32_e32 v204, v204
	v_rcp_f32_e32 v205, v205
	v_lshlrev_b32_e32 v206, 16, v141
	v_and_b32_e32 v207, 0xffff0000, v141
	v_pk_mul_f32 v[204:205], v[206:207], v[204:205]
	v_pk_mul_f32 v[32:33], v[32:33], v[204:205]
	v_lshlrev_b32_e32 v204, 16, v142
	v_and_b32_e32 v205, 0xffff0000, v142
	v_rcp_f32_e32 v204, v204
	v_rcp_f32_e32 v205, v205
	v_lshlrev_b32_e32 v206, 16, v146
	v_and_b32_e32 v207, 0xffff0000, v146
	v_pk_mul_f32 v[204:205], v[206:207], v[204:205]
	v_pk_mul_f32 v[26:27], v[26:27], v[204:205]
	v_lshlrev_b32_e32 v204, 16, v143
	v_and_b32_e32 v205, 0xffff0000, v143
	v_rcp_f32_e32 v204, v204
	v_rcp_f32_e32 v205, v205
	v_lshlrev_b32_e32 v206, 16, v147
	v_and_b32_e32 v207, 0xffff0000, v147
	v_pk_mul_f32 v[204:205], v[206:207], v[204:205]
	v_pk_mul_f32 v[28:29], v[28:29], v[204:205]
	v_lshlrev_b32_e32 v204, 16, v144
	v_and_b32_e32 v205, 0xffff0000, v144
	v_rcp_f32_e32 v204, v204
	v_rcp_f32_e32 v205, v205
	v_lshlrev_b32_e32 v206, 16, v148
	v_and_b32_e32 v207, 0xffff0000, v148
	v_pk_mul_f32 v[204:205], v[206:207], v[204:205]
	v_pk_mul_f32 v[22:23], v[22:23], v[204:205]
	v_lshlrev_b32_e32 v204, 16, v145
	v_and_b32_e32 v205, 0xffff0000, v145
	v_rcp_f32_e32 v204, v204
	v_rcp_f32_e32 v205, v205
	v_lshlrev_b32_e32 v206, 16, v149
	v_and_b32_e32 v207, 0xffff0000, v149
	v_pk_mul_f32 v[204:205], v[206:207], v[204:205]
	v_pk_mul_f32 v[24:25], v[24:25], v[204:205]
	s_waitcnt vmcnt(0)
	v_lshlrev_b32_e32 v204, 16, v150
	v_and_b32_e32 v205, 0xffff0000, v150
	v_rcp_f32_e32 v204, v204
	v_rcp_f32_e32 v205, v205
	v_lshlrev_b32_e32 v206, 16, v154
	v_and_b32_e32 v207, 0xffff0000, v154
	v_pk_mul_f32 v[204:205], v[206:207], v[204:205]
	v_pk_mul_f32 v[18:19], v[18:19], v[204:205]
	v_lshlrev_b32_e32 v204, 16, v151
	v_and_b32_e32 v205, 0xffff0000, v151
	v_rcp_f32_e32 v204, v204
	v_rcp_f32_e32 v205, v205
	v_lshlrev_b32_e32 v206, 16, v155
	v_and_b32_e32 v207, 0xffff0000, v155
	v_pk_mul_f32 v[204:205], v[206:207], v[204:205]
	v_pk_mul_f32 v[20:21], v[20:21], v[204:205]
	v_lshlrev_b32_e32 v204, 16, v152
	v_and_b32_e32 v205, 0xffff0000, v152
	v_rcp_f32_e32 v204, v204
	v_rcp_f32_e32 v205, v205
	v_lshlrev_b32_e32 v206, 16, v156
	v_and_b32_e32 v207, 0xffff0000, v156
	v_pk_mul_f32 v[204:205], v[206:207], v[204:205]
	v_pk_mul_f32 v[14:15], v[14:15], v[204:205]
	v_lshlrev_b32_e32 v204, 16, v153
	v_and_b32_e32 v205, 0xffff0000, v153
	v_rcp_f32_e32 v204, v204
	v_rcp_f32_e32 v205, v205
	v_lshlrev_b32_e32 v206, 16, v157
	v_and_b32_e32 v207, 0xffff0000, v157
	v_pk_mul_f32 v[204:205], v[206:207], v[204:205]
	v_pk_mul_f32 v[16:17], v[16:17], v[204:205]
	v_lshlrev_b32_e32 v204, 16, v174
	v_and_b32_e32 v205, 0xffff0000, v174
	v_rcp_f32_e32 v204, v204
	v_rcp_f32_e32 v205, v205
	v_lshlrev_b32_e32 v206, 16, v178
	v_and_b32_e32 v207, 0xffff0000, v178
	v_pk_mul_f32 v[204:205], v[206:207], v[204:205]
	v_pk_mul_f32 v[10:11], v[10:11], v[204:205]
	v_lshlrev_b32_e32 v204, 16, v175
	v_and_b32_e32 v205, 0xffff0000, v175
	v_rcp_f32_e32 v204, v204
	v_rcp_f32_e32 v205, v205
	v_lshlrev_b32_e32 v206, 16, v179
	v_and_b32_e32 v207, 0xffff0000, v179
	v_pk_mul_f32 v[204:205], v[206:207], v[204:205]
	v_pk_mul_f32 v[12:13], v[12:13], v[204:205]
	v_lshlrev_b32_e32 v204, 16, v176
	v_and_b32_e32 v205, 0xffff0000, v176
	v_rcp_f32_e32 v204, v204
	v_rcp_f32_e32 v205, v205
	v_lshlrev_b32_e32 v206, 16, v180
	v_and_b32_e32 v207, 0xffff0000, v180
	v_pk_mul_f32 v[204:205], v[206:207], v[204:205]
	v_pk_mul_f32 v[6:7], v[6:7], v[204:205]
	v_lshlrev_b32_e32 v204, 16, v177
	v_and_b32_e32 v205, 0xffff0000, v177
	v_rcp_f32_e32 v204, v204
	v_rcp_f32_e32 v205, v205
	v_lshlrev_b32_e32 v206, 16, v181
	v_and_b32_e32 v207, 0xffff0000, v181
	v_pk_mul_f32 v[204:205], v[206:207], v[204:205]
	v_pk_mul_f32 v[8:9], v[8:9], v[204:205]
